# lazy out epilogue back to row-group-major tile order (both 64B halves of each residual line touched by consecutive instructions), 13-deep prefetch, all gamma/beta resident
# speedup vs baseline: 1.0046x; 1.0046x over previous
; #define PG8_STAGE(bufoff, gbase, voff) do { _Pragma("unroll") for (int _i = 0; _i < 2; ++_i) \
;         __builtin_amdgcn_global_load_lds((const unsigned*)((const char*)(gbase) + (voff)[_i]), (PG8_LAS unsigned*)(lds + (bufoff) + ldsw + _i * 8192), 16, 0, 0); } while (0)
; #define PG8_LDA(dst, b, h) do { _Pragma("unroll") for (int m = 0; m < 4; ++m) _Pragma("unroll") for (int k = 0; k < 2; ++k) dst[m][k] = *(const PG8_LAS bf16x8*)(lds + PG8_SA(b, h) + aoff + m * 2048 + k * 1024); } while (0)
; #define PG8_LDB(dst, b, h) do { _Pragma("unroll") for (int n = 0; n < 2; ++n) _Pragma("unroll") for (int k = 0; k < 2; ++k) dst[n][k] = *(const PG8_LAS bf16x8*)(lds + PG8_SB(b, h) + boff + n * 2048 + k * 1024); } while (0)
; #define PG8_MMA(ai, bj, At, Bt) do { __builtin_amdgcn_s_setprio(1); _Pragma("unroll") for (int m = 0; m < 4; ++m) _Pragma("unroll") for (int n = 0; n < 2; ++n) _Pragma("unroll") for (int k = 0; k < 2; ++k) \
;         acc[ai][bj][m][n] = __builtin_amdgcn_mfma_f32_16x16x32_bf16(Bt[n][k], At[m][k], acc[ai][bj][m][n], 0, 0, 0); __builtin_amdgcn_s_setprio(0); } while (0)
; #define PG8_WAIT_V(n) asm volatile("s_waitcnt vmcnt(" #n ")" ::: "memory")
; #define PG8_WAIT_L(n) asm volatile("s_waitcnt lgkmcnt(" #n ")" ::: "memory")
; #define PG8_BAR __builtin_amdgcn_s_barrier()
; #define PG8_SCHED __builtin_amdgcn_sched_barrier(0)
; template <class Epi, class Sched>
; __device__ __forceinline__ void gemm_phase(PG8_LAS unsigned char* lds, const Gemm g, const Sched& S, const Epi& E) {
;     ...
;             PG8_LDB(B0, 0, 0); PG8_SCHED; PG8_LDA(At, 0, 0); PG8_STAGE(PG8_SA(1, 1), a1 + hstep, voffA);
;             PG8_WAIT_L(8); PG8_BAR; PG8_WAIT_L(0); PG8_MMA(0, 0, At, B0); PG8_BAR; PG8_SCHED;
;             PG8_LDB(B1, 0, 1); PG8_STAGE(PG8_SB(0, 0), b2, voffB);
;             PG8_BAR; PG8_WAIT_L(0); PG8_MMA(0, 1, At, B1); PG8_BAR;
;             PG8_LDA(At, 0, 1); PG8_STAGE(PG8_SA(0, 0), a2, voffA);
;             PG8_BAR; PG8_WAIT_L(0); PG8_MMA(1, 0, At, B0); PG8_BAR; PG8_SCHED;
;             PG8_STAGE(PG8_SB(0, 1), b2 + hstep, voffB);
;             PG8_WAIT_V(6); PG8_BAR; PG8_MMA(1, 1, At, B1); PG8_BAR;
.LBB0_2754:
	s_add_u32 s14, s12, 0xfffc0080
	s_addc_u32 s15, s13, -1
	s_add_i32 s37, 0, 0x10000
	v_add_u32_e32 v140, s37, v142
	ds_read_b128 v[144:147], v140
	ds_read_b128 v[148:151], v140 offset:1024
	ds_read_b128 v[162:165], v140 offset:2048
	ds_read_b128 v[166:169], v140 offset:3072
	s_cmp_eq_u32 s36, 12
	s_cselect_b32 s17, s5, s15
	s_cselect_b32 s16, s31, s14
	s_cselect_b32 s15, s3, s35
	s_cselect_b32 s14, s33, s34
	v_lshl_add_u64 v[140:141], s[12:13], 0, v[136:137]
	s_add_i32 m0, s23, 0xc000
	ds_read_b128 v[170:173], v143
	ds_read_b128 v[174:177], v143 offset:1024
	ds_read_b128 v[178:181], v143 offset:2048
	ds_read_b128 v[188:191], v143 offset:3072
	ds_read_b128 v[192:195], v143 offset:4096
	ds_read_b128 v[196:199], v143 offset:5120
	ds_read_b128 v[200:203], v143 offset:6144
	ds_read_b128 v[204:207], v143 offset:7168
	global_load_lds_dwordx4 v[140:141], off
	v_lshl_add_u64 v[140:141], s[12:13], 0, v[138:139]
	s_add_i32 m0, s23, 0xe000
	s_nop 0
	global_load_lds_dwordx4 v[140:141], off
	s_waitcnt lgkmcnt(8)
	s_barrier
	s_waitcnt lgkmcnt(0)
	s_setprio 1
	s_waitcnt lgkmcnt(0)
	v_mfma_f32_16x16x32_bf16 v[130:133], v[144:147], v[170:173], v[130:133]
	v_mfma_f32_16x16x32_bf16 v[126:129], v[162:165], v[170:173], v[126:129]
	v_mfma_f32_16x16x32_bf16 v[114:117], v[144:147], v[178:181], v[114:117]
	v_mfma_f32_16x16x32_bf16 v[110:113], v[162:165], v[178:181], v[110:113]
	v_mfma_f32_16x16x32_bf16 v[98:101], v[144:147], v[192:195], v[98:101]
	v_mfma_f32_16x16x32_bf16 v[94:97], v[162:165], v[192:195], v[94:97]
	v_mfma_f32_16x16x32_bf16 v[82:85], v[144:147], v[200:203], v[82:85]
	v_mfma_f32_16x16x32_bf16 v[78:81], v[162:165], v[200:203], v[78:81]
	v_mfma_f32_16x16x32_bf16 v[130:133], v[148:151], v[174:177], v[130:133]
	v_mfma_f32_16x16x32_bf16 v[126:129], v[166:169], v[174:177], v[126:129]
	v_mfma_f32_16x16x32_bf16 v[114:117], v[148:151], v[188:191], v[114:117]
	v_mfma_f32_16x16x32_bf16 v[110:113], v[166:169], v[188:191], v[110:113]
	v_mfma_f32_16x16x32_bf16 v[98:101], v[148:151], v[196:199], v[98:101]
	v_mfma_f32_16x16x32_bf16 v[94:97], v[166:169], v[196:199], v[94:97]
	v_mfma_f32_16x16x32_bf16 v[82:85], v[148:151], v[204:207], v[82:85]
	v_mfma_f32_16x16x32_bf16 v[78:81], v[166:169], v[204:207], v[78:81]
	s_setprio 0
	s_barrier
	s_add_i32 s40, 0, 0x14000
	v_add_u32_e32 v140, s40, v142
	s_add_i32 s37, s37, s21
	ds_read_b128 v[208:211], v140
	ds_read_b128 v[212:215], v140 offset:1024
	ds_read_b128 v[216:219], v140 offset:2048
	ds_read_b128 v[220:223], v140 offset:3072
	v_lshl_add_u64 v[140:141], s[14:15], 0, v[134:135]
	s_mov_b32 m0, s37
	v_lshl_add_u64 v[154:155], s[14:15], 0, v[18:19]
	global_load_lds_dwordx4 v[140:141], off
	s_add_i32 m0, s37, 0x2000
	s_nop 0
	global_load_lds_dwordx4 v[154:155], off
	s_barrier
	s_waitcnt lgkmcnt(0)
	s_setprio 1
	s_waitcnt lgkmcnt(0)
	v_mfma_f32_16x16x32_bf16 v[122:125], v[208:211], v[170:173], v[122:125]
	v_mfma_f32_16x16x32_bf16 v[118:121], v[216:219], v[170:173], v[118:121]
	v_mfma_f32_16x16x32_bf16 v[106:109], v[208:211], v[178:181], v[106:109]
	v_mfma_f32_16x16x32_bf16 v[102:105], v[216:219], v[178:181], v[102:105]
	v_mfma_f32_16x16x32_bf16 v[90:93], v[208:211], v[192:195], v[90:93]
	v_mfma_f32_16x16x32_bf16 v[86:89], v[216:219], v[192:195], v[86:89]
	v_mfma_f32_16x16x32_bf16 v[74:77], v[208:211], v[200:203], v[74:77]
	v_mfma_f32_16x16x32_bf16 v[70:73], v[216:219], v[200:203], v[70:73]
	v_mfma_f32_16x16x32_bf16 v[122:125], v[212:215], v[174:177], v[122:125]
	v_mfma_f32_16x16x32_bf16 v[118:121], v[220:223], v[174:177], v[118:121]
	v_mfma_f32_16x16x32_bf16 v[106:109], v[212:215], v[188:191], v[106:109]
	v_mfma_f32_16x16x32_bf16 v[102:105], v[220:223], v[188:191], v[102:105]
	v_mfma_f32_16x16x32_bf16 v[90:93], v[212:215], v[196:199], v[90:93]
	v_mfma_f32_16x16x32_bf16 v[86:89], v[220:223], v[196:199], v[86:89]
	v_mfma_f32_16x16x32_bf16 v[74:77], v[212:215], v[204:207], v[74:77]
	v_mfma_f32_16x16x32_bf16 v[70:73], v[220:223], v[204:207], v[70:73]
	s_setprio 0
	s_mov_b32 m0, s23
	v_lshl_add_u64 v[156:157], s[16:17], 0, v[134:135]
	s_barrier
	ds_read_b128 v[170:173], v143 offset:16384
	ds_read_b128 v[174:177], v143 offset:17408
	ds_read_b128 v[178:181], v143 offset:18432
	ds_read_b128 v[188:191], v143 offset:19456
	ds_read_b128 v[192:195], v143 offset:20480
	ds_read_b128 v[196:199], v143 offset:21504
	ds_read_b128 v[200:203], v143 offset:22528
	ds_read_b128 v[204:207], v143 offset:23552
	global_load_lds_dwordx4 v[156:157], off
	v_lshl_add_u64 v[186:187], s[16:17], 0, v[18:19]
	s_mov_b32 m0, s24
	s_nop 0
	global_load_lds_dwordx4 v[186:187], off
	s_barrier
	s_waitcnt lgkmcnt(0)
	s_setprio 1
	s_waitcnt lgkmcnt(0)
	v_mfma_f32_16x16x32_bf16 v[66:69], v[144:147], v[170:173], v[66:69]
	v_mfma_f32_16x16x32_bf16 v[62:65], v[162:165], v[170:173], v[62:65]
	v_mfma_f32_16x16x32_bf16 v[50:53], v[144:147], v[178:181], v[50:53]
	v_mfma_f32_16x16x32_bf16 v[46:49], v[162:165], v[178:181], v[46:49]
	v_mfma_f32_16x16x32_bf16 v[34:37], v[144:147], v[192:195], v[34:37]
	v_mfma_f32_16x16x32_bf16 v[30:33], v[162:165], v[192:195], v[30:33]
	v_mfma_f32_16x16x32_bf16 v[12:15], v[144:147], v[200:203], v[12:15]
	v_mfma_f32_16x16x32_bf16 v[8:11], v[162:165], v[200:203], v[8:11]
	v_mfma_f32_16x16x32_bf16 v[66:69], v[148:151], v[174:177], v[66:69]
	v_mfma_f32_16x16x32_bf16 v[62:65], v[166:169], v[174:177], v[62:65]
	v_mfma_f32_16x16x32_bf16 v[50:53], v[148:151], v[188:191], v[50:53]
	v_mfma_f32_16x16x32_bf16 v[46:49], v[166:169], v[188:191], v[46:49]
	v_mfma_f32_16x16x32_bf16 v[34:37], v[148:151], v[196:199], v[34:37]
	v_mfma_f32_16x16x32_bf16 v[30:33], v[166:169], v[196:199], v[30:33]
	v_mfma_f32_16x16x32_bf16 v[12:15], v[148:151], v[204:207], v[12:15]
	v_mfma_f32_16x16x32_bf16 v[8:11], v[166:169], v[204:207], v[8:11]
	s_setprio 0
	s_barrier
; #define PG8_STAGE(bufoff, gbase, voff) do { _Pragma("unroll") for (int _i = 0; _i < 2; ++_i) \
;         __builtin_amdgcn_global_load_lds((const unsigned*)((const char*)(gbase) + (voff)[_i]), (PG8_LAS unsigned*)(lds + (bufoff) + ldsw + _i * 8192), 16, 0, 0); } while (0)
; #define PG8_LDA(dst, b, h) do { _Pragma("unroll") for (int m = 0; m < 4; ++m) _Pragma("unroll") for (int k = 0; k < 2; ++k) dst[m][k] = *(const PG8_LAS bf16x8*)(lds + PG8_SA(b, h) + aoff + m * 2048 + k * 1024); } while (0)
; #define PG8_LDB(dst, b, h) do { _Pragma("unroll") for (int n = 0; n < 2; ++n) _Pragma("unroll") for (int k = 0; k < 2; ++k) dst[n][k] = *(const PG8_LAS bf16x8*)(lds + PG8_SB(b, h) + boff + n * 2048 + k * 1024); } while (0)
; #define PG8_MMA(ai, bj, At, Bt) do { __builtin_amdgcn_s_setprio(1); _Pragma("unroll") for (int m = 0; m < 4; ++m) _Pragma("unroll") for (int n = 0; n < 2; ++n) _Pragma("unroll") for (int k = 0; k < 2; ++k) \
;         acc[ai][bj][m][n] = __builtin_amdgcn_mfma_f32_16x16x32_bf16(Bt[n][k], At[m][k], acc[ai][bj][m][n], 0, 0, 0); __builtin_amdgcn_s_setprio(0); } while (0)
; #define PG8_WAIT_V(n) asm volatile("s_waitcnt vmcnt(" #n ")" ::: "memory")
; #define PG8_WAIT_L(n) asm volatile("s_waitcnt lgkmcnt(" #n ")" ::: "memory")
; #define PG8_BAR __builtin_amdgcn_s_barrier()
; #define PG8_SCHED __builtin_amdgcn_sched_barrier(0)
; template <class Epi, class Sched>
; __device__ __forceinline__ void gemm_phase(PG8_LAS unsigned char* lds, const Gemm g, const Sched& S, const Epi& E) {
;     ...
;             PG8_WAIT_V(6); PG8_BAR; PG8_MMA(1, 1, At, B1); PG8_BAR;
;             PG8_LDB(B0, 1, 0); PG8_SCHED; PG8_LDA(At, 1, 0); PG8_STAGE(PG8_SA(0, 1), a2 + hstep, voffA);
;             PG8_WAIT_L(8); PG8_BAR; PG8_WAIT_L(0); PG8_MMA(0, 0, At, B0); PG8_BAR; PG8_SCHED;
;             PG8_LDB(B1, 1, 1); PG8_STAGE(PG8_SB(1, 0), b3, voffB);
;             PG8_BAR; PG8_WAIT_L(0); PG8_MMA(0, 1, At, B1); PG8_BAR;
;             PG8_LDA(At, 1, 1); PG8_STAGE(PG8_SA(1, 0), a3, voffA);
;             PG8_BAR; PG8_WAIT_L(0); PG8_MMA(1, 0, At, B0); PG8_BAR; PG8_SCHED;
	s_add_u32 s38, s14, 0x40000
	s_addc_u32 s39, s15, 0
	s_add_i32 s37, s40, s21
	v_lshl_add_u64 v[144:145], s[38:39], 0, v[134:135]
	s_mov_b32 m0, s37
	s_nop 0
	global_load_lds_dwordx4 v[144:145], off
	v_lshl_add_u64 v[144:145], s[38:39], 0, v[18:19]
	s_add_i32 m0, s37, 0x2000
	s_nop 0
	global_load_lds_dwordx4 v[144:145], off
	s_waitcnt vmcnt(6)
	s_barrier
	s_setprio 1
	v_mfma_f32_16x16x32_bf16 v[58:61], v[208:211], v[170:173], v[58:61]
	v_mfma_f32_16x16x32_bf16 v[54:57], v[216:219], v[170:173], v[54:57]
	v_mfma_f32_16x16x32_bf16 v[42:45], v[208:211], v[178:181], v[42:45]
	v_mfma_f32_16x16x32_bf16 v[38:41], v[216:219], v[178:181], v[38:41]
	v_mfma_f32_16x16x32_bf16 v[26:29], v[208:211], v[192:195], v[26:29]
	v_mfma_f32_16x16x32_bf16 v[22:25], v[216:219], v[192:195], v[22:25]
	v_mfma_f32_16x16x32_bf16 v[4:7], v[208:211], v[200:203], v[4:7]
	v_mfma_f32_16x16x32_bf16 v[0:3], v[216:219], v[200:203], v[0:3]
	v_mfma_f32_16x16x32_bf16 v[58:61], v[212:215], v[174:177], v[58:61]
	v_mfma_f32_16x16x32_bf16 v[54:57], v[220:223], v[174:177], v[54:57]
	v_mfma_f32_16x16x32_bf16 v[42:45], v[212:215], v[188:191], v[42:45]
	v_mfma_f32_16x16x32_bf16 v[38:41], v[220:223], v[188:191], v[38:41]
	v_mfma_f32_16x16x32_bf16 v[26:29], v[212:215], v[196:199], v[26:29]
	v_mfma_f32_16x16x32_bf16 v[22:25], v[220:223], v[196:199], v[22:25]
	v_mfma_f32_16x16x32_bf16 v[4:7], v[212:215], v[204:207], v[4:7]
	v_mfma_f32_16x16x32_bf16 v[0:3], v[220:223], v[204:207], v[0:3]
	s_setprio 0
	s_add_i32 s37, 0, 0x18000
	v_add_u32_e32 v166, s37, v142
	s_barrier
	ds_read_b128 v[144:147], v166
	ds_read_b128 v[148:151], v166 offset:1024
	ds_read_b128 v[162:165], v166 offset:2048
	ds_read_b128 v[166:169], v166 offset:3072
	s_add_u32 s16, s16, 0x40000
	s_addc_u32 s17, s17, 0
	s_mov_b32 m0, s25
	v_lshl_add_u64 v[208:209], s[16:17], 0, v[134:135]
	ds_read_b128 v[170:173], v143 offset:32768
	ds_read_b128 v[174:177], v143 offset:33792
	ds_read_b128 v[178:181], v143 offset:34816
	ds_read_b128 v[188:191], v143 offset:35840
	ds_read_b128 v[192:195], v143 offset:36864
	ds_read_b128 v[196:199], v143 offset:37888
	ds_read_b128 v[200:203], v143 offset:38912
	ds_read_b128 v[204:207], v143 offset:39936
	global_load_lds_dwordx4 v[208:209], off
	v_lshl_add_u64 v[208:209], s[16:17], 0, v[18:19]
	s_mov_b32 m0, s26
	s_nop 0
	global_load_lds_dwordx4 v[208:209], off
	s_waitcnt lgkmcnt(8)
	s_barrier
	s_waitcnt lgkmcnt(0)
	s_setprio 1
	s_waitcnt lgkmcnt(0)
	v_mfma_f32_16x16x32_bf16 v[130:133], v[144:147], v[170:173], v[130:133]
	v_mfma_f32_16x16x32_bf16 v[126:129], v[162:165], v[170:173], v[126:129]
	v_mfma_f32_16x16x32_bf16 v[114:117], v[144:147], v[178:181], v[114:117]
	v_mfma_f32_16x16x32_bf16 v[110:113], v[162:165], v[178:181], v[110:113]
	v_mfma_f32_16x16x32_bf16 v[98:101], v[144:147], v[192:195], v[98:101]
	v_mfma_f32_16x16x32_bf16 v[94:97], v[162:165], v[192:195], v[94:97]
	v_mfma_f32_16x16x32_bf16 v[82:85], v[144:147], v[200:203], v[82:85]
	v_mfma_f32_16x16x32_bf16 v[78:81], v[162:165], v[200:203], v[78:81]
	v_mfma_f32_16x16x32_bf16 v[130:133], v[148:151], v[174:177], v[130:133]
	v_mfma_f32_16x16x32_bf16 v[126:129], v[166:169], v[174:177], v[126:129]
	v_mfma_f32_16x16x32_bf16 v[114:117], v[148:151], v[188:191], v[114:117]
	v_mfma_f32_16x16x32_bf16 v[110:113], v[166:169], v[188:191], v[110:113]
	v_mfma_f32_16x16x32_bf16 v[98:101], v[148:151], v[196:199], v[98:101]
	v_mfma_f32_16x16x32_bf16 v[94:97], v[166:169], v[196:199], v[94:97]
	v_mfma_f32_16x16x32_bf16 v[82:85], v[148:151], v[204:207], v[82:85]
	v_mfma_f32_16x16x32_bf16 v[78:81], v[166:169], v[204:207], v[78:81]
	s_setprio 0
	s_barrier
	s_add_i32 s16, 0, 0x1c000
	s_add_i32 s17, s37, s21
	v_add_u32_e32 v220, s16, v142
	v_lshl_add_u64 v[140:141], v[140:141], 0, s[42:43]
	s_mov_b32 m0, s17
	ds_read_b128 v[208:211], v220
	ds_read_b128 v[212:215], v220 offset:1024
	ds_read_b128 v[216:219], v220 offset:2048
	ds_read_b128 v[220:223], v220 offset:3072
	global_load_lds_dwordx4 v[140:141], off
	v_lshl_add_u64 v[140:141], v[154:155], 0, s[42:43]
	s_add_i32 m0, s17, 0x2000
	s_nop 0
	global_load_lds_dwordx4 v[140:141], off
	s_barrier
	s_waitcnt lgkmcnt(0)
	s_setprio 1
	s_waitcnt lgkmcnt(0)
	v_mfma_f32_16x16x32_bf16 v[122:125], v[208:211], v[170:173], v[122:125]
	v_mfma_f32_16x16x32_bf16 v[118:121], v[216:219], v[170:173], v[118:121]
	v_mfma_f32_16x16x32_bf16 v[106:109], v[208:211], v[178:181], v[106:109]
	v_mfma_f32_16x16x32_bf16 v[102:105], v[216:219], v[178:181], v[102:105]
	v_mfma_f32_16x16x32_bf16 v[90:93], v[208:211], v[192:195], v[90:93]
	v_mfma_f32_16x16x32_bf16 v[86:89], v[216:219], v[192:195], v[86:89]
	v_mfma_f32_16x16x32_bf16 v[74:77], v[208:211], v[200:203], v[74:77]
	v_mfma_f32_16x16x32_bf16 v[70:73], v[216:219], v[200:203], v[70:73]
	v_mfma_f32_16x16x32_bf16 v[122:125], v[212:215], v[174:177], v[122:125]
	v_mfma_f32_16x16x32_bf16 v[118:121], v[220:223], v[174:177], v[118:121]
	v_mfma_f32_16x16x32_bf16 v[106:109], v[212:215], v[188:191], v[106:109]
	v_mfma_f32_16x16x32_bf16 v[102:105], v[220:223], v[188:191], v[102:105]
	v_mfma_f32_16x16x32_bf16 v[90:93], v[212:215], v[196:199], v[90:93]
	v_mfma_f32_16x16x32_bf16 v[86:89], v[220:223], v[196:199], v[86:89]
	v_mfma_f32_16x16x32_bf16 v[74:77], v[212:215], v[204:207], v[74:77]
	v_mfma_f32_16x16x32_bf16 v[70:73], v[220:223], v[204:207], v[70:73]
	s_setprio 0
	s_mov_b32 m0, s27
	v_lshl_add_u64 v[140:141], v[156:157], 0, s[42:43]
	s_barrier
	ds_read_b128 v[170:173], v143 offset:49152
	ds_read_b128 v[174:177], v143 offset:50176
	ds_read_b128 v[178:181], v143 offset:51200
	ds_read_b128 v[188:191], v143 offset:52224
	ds_read_b128 v[192:195], v143 offset:53248
	ds_read_b128 v[196:199], v143 offset:54272
	ds_read_b128 v[200:203], v143 offset:55296
	ds_read_b128 v[204:207], v143 offset:56320
	global_load_lds_dwordx4 v[140:141], off
	v_lshl_add_u64 v[140:141], v[186:187], 0, s[42:43]
	s_mov_b32 m0, s28
	s_nop 0
	global_load_lds_dwordx4 v[140:141], off
	s_barrier
; DI bf16x4 pack4(float a, float b, float c, float d) { u32x2v u; u.x = pk2(a, b); u.y = pk2(c, d); return __builtin_bit_cast(bf16x4, u); }
; #define PG8_WAIT_V(n) asm volatile("s_waitcnt vmcnt(" #n ")" ::: "memory")
; #define PG8_WAIT_L(n) asm volatile("s_waitcnt lgkmcnt(" #n ")" ::: "memory")
; template <class Epi, class Sched>
; __device__ __forceinline__ void gemm_phase(PG8_LAS unsigned char* lds, const Gemm g, const Sched& S, const Epi& E) {
;     ...
;             PG8_WAIT_V(6); PG8_BAR; PG8_MMA(1, 1, At, B1); PG8_BAR;
;             PG8_LDB(B0, 1, 0); PG8_SCHED; PG8_LDA(At, 1, 0); PG8_STAGE(PG8_SA(0, 1), a2 + hstep, voffA);
;             PG8_WAIT_L(8); PG8_BAR; PG8_WAIT_L(0); PG8_MMA(0, 0, At, B0); PG8_BAR; PG8_SCHED;
;             PG8_LDB(B1, 1, 1); PG8_STAGE(PG8_SB(1, 0), b3, voffB);
;             PG8_BAR; PG8_WAIT_L(0); PG8_MMA(0, 1, At, B1); PG8_BAR;
;             PG8_LDA(At, 1, 1); PG8_STAGE(PG8_SA(1, 0), a3, voffA);
;             PG8_BAR; PG8_WAIT_L(0); PG8_MMA(1, 0, At, B0); PG8_BAR; PG8_SCHED;
;             PG8_STAGE(PG8_SB(1, 1), b3 + hstep, voffB);
;             PG8_WAIT_V(6); PG8_BAR; PG8_MMA(1, 1, At, B1); PG8_BAR;
;   DI void operator()(const f32x4 (&acc)[2][2][4][2], const pg8::Unit& u, int wr, int wc, int fr, int fq) const {
;     bf16_t* MERGED = (reinterpret_cast<bf16_t*>(p.ws + OFF_GA));
; #pragma unroll
;     for (int ai = 0; ai < 2; ++ai)
; #pragma unroll
;       for (int m = 0; m < 4; ++m) {
;         const int row = u.pm * 256 + 128 * ai + 64 * wr + 16 * m + fr;
; #pragma unroll
;         for (int bj = 0; bj < 2; ++bj)
; #pragma unroll
;           for (int n = 0; n < 2; ++n) {
;             const size_t idx = (size_t)row * 1024 + u.pn * 256 + 128 * bj + 32 * wc + 16 * n + 4 * fq;
;             const f32x4 a = acc[ai][bj][m][n];
;             if (MODE == 0) {
;               const unsigned g = *reinterpret_cast<const unsigned*>(reinterpret_cast<const unsigned char*>(p.ws + OFF_RB) + idx);
;               const float k = 1.f / 255.f;
;               st4(MERGED + idx, pack4((float)(g & 255u) * k * a[0], (float)((g >> 8) & 255u) * k * a[1], (float)((g >> 16) & 255u) * k * a[2], (float)(g >> 24) * k * a[3]));
;             } else {
;               f32x4 x = *reinterpret_cast<const f32x4*>(p.out + idx);
;               x = x * ALPHA + a;
;               *reinterpret_cast<f32x4*>(p.out + idx) = x;
;             }
	s_waitcnt lgkmcnt(0)
	s_setprio 1
	s_waitcnt lgkmcnt(0)
	v_mfma_f32_16x16x32_bf16 v[66:69], v[144:147], v[170:173], v[66:69]
	v_mfma_f32_16x16x32_bf16 v[62:65], v[162:165], v[170:173], v[62:65]
	v_mfma_f32_16x16x32_bf16 v[50:53], v[144:147], v[178:181], v[50:53]
	v_mfma_f32_16x16x32_bf16 v[46:49], v[162:165], v[178:181], v[46:49]
	v_mfma_f32_16x16x32_bf16 v[34:37], v[144:147], v[192:195], v[34:37]
	v_mfma_f32_16x16x32_bf16 v[30:33], v[162:165], v[192:195], v[30:33]
	v_mfma_f32_16x16x32_bf16 v[12:15], v[144:147], v[200:203], v[12:15]
	v_mfma_f32_16x16x32_bf16 v[8:11], v[162:165], v[200:203], v[8:11]
	v_mfma_f32_16x16x32_bf16 v[66:69], v[148:151], v[174:177], v[66:69]
	v_mfma_f32_16x16x32_bf16 v[62:65], v[166:169], v[174:177], v[62:65]
	v_mfma_f32_16x16x32_bf16 v[50:53], v[148:151], v[188:191], v[50:53]
	v_mfma_f32_16x16x32_bf16 v[46:49], v[166:169], v[188:191], v[46:49]
	v_mfma_f32_16x16x32_bf16 v[34:37], v[148:151], v[196:199], v[34:37]
	v_mfma_f32_16x16x32_bf16 v[30:33], v[166:169], v[196:199], v[30:33]
	v_mfma_f32_16x16x32_bf16 v[12:15], v[148:151], v[204:207], v[12:15]
	v_mfma_f32_16x16x32_bf16 v[8:11], v[166:169], v[204:207], v[8:11]
	s_setprio 0
	s_barrier
	s_add_u32 s14, s14, 0x40080
	s_addc_u32 s15, s15, 0
	s_add_i32 s16, s16, s21
	v_lshl_add_u64 v[140:141], s[14:15], 0, v[134:135]
	s_mov_b32 m0, s16
	s_nop 0
	global_load_lds_dwordx4 v[140:141], off
	v_lshl_add_u64 v[140:141], s[14:15], 0, v[18:19]
	s_add_i32 m0, s16, 0x2000
	s_nop 0
	global_load_lds_dwordx4 v[140:141], off
	s_waitcnt vmcnt(6)
	s_barrier
	s_setprio 1
	v_mfma_f32_16x16x32_bf16 v[58:61], v[208:211], v[170:173], v[58:61]
	v_mfma_f32_16x16x32_bf16 v[54:57], v[216:219], v[170:173], v[54:57]
	v_mfma_f32_16x16x32_bf16 v[42:45], v[208:211], v[178:181], v[42:45]
	v_mfma_f32_16x16x32_bf16 v[38:41], v[216:219], v[178:181], v[38:41]
	v_mfma_f32_16x16x32_bf16 v[26:29], v[208:211], v[192:195], v[26:29]
	v_mfma_f32_16x16x32_bf16 v[22:25], v[216:219], v[192:195], v[22:25]
	v_mfma_f32_16x16x32_bf16 v[4:7], v[208:211], v[200:203], v[4:7]
	v_mfma_f32_16x16x32_bf16 v[0:3], v[216:219], v[200:203], v[0:3]
	v_mfma_f32_16x16x32_bf16 v[58:61], v[212:215], v[174:177], v[58:61]
	v_mfma_f32_16x16x32_bf16 v[54:57], v[220:223], v[174:177], v[54:57]
	v_mfma_f32_16x16x32_bf16 v[42:45], v[212:215], v[188:191], v[42:45]
	v_mfma_f32_16x16x32_bf16 v[38:41], v[220:223], v[188:191], v[38:41]
	v_mfma_f32_16x16x32_bf16 v[26:29], v[212:215], v[196:199], v[26:29]
	v_mfma_f32_16x16x32_bf16 v[22:25], v[220:223], v[196:199], v[22:25]
	v_mfma_f32_16x16x32_bf16 v[4:7], v[212:215], v[204:207], v[4:7]
	v_mfma_f32_16x16x32_bf16 v[0:3], v[220:223], v[204:207], v[0:3]
	s_setprio 0
	s_add_i32 s36, s36, 2
	s_add_u32 s12, s12, 0x100
	s_addc_u32 s13, s13, 0
	s_add_u32 s34, s34, 0x100
	s_addc_u32 s35, s35, 0
	s_cmp_gt_u32 s36, 13
	s_barrier
	s_cbranch_scc0 .LBB0_2754
	v_readlane_b32 s12, v251, 8
	s_cmp_eq_u32 s12, 0
	s_cbranch_scc1 .Llz_plain
	v_lshl_add_u32 v140, s10, 8, v21
	s_lshl_b32 s10, s11, 10
	v_readlane_b32 s14, v249, 4
	v_readlane_b32 s15, v249, 5
	v_readlane_b32 s13, v251, 6
	s_mov_b32 s16, 0x3fd744fd
	v_lshlrev_b32_e32 v141, 3, v140
	s_add_i32 s10, s10, s13
	s_add_i32 s12, s12, -1
	s_lshl_b32 s12, s12, 12
	v_add_u32_e32 v144, s10, v16
	v_readlane_b32 s72, v249, 38
	v_readlane_b32 s73, v249, 39
	v_readlane_b32 s74, v249, 40
	v_readlane_b32 s75, v249, 41
	v_readlane_b32 s76, v249, 0
	v_readlane_b32 s77, v249, 1
	v_lshl_add_u32 v140, v140, 12, v144
	s_add_u32 s72, s72, s12
	s_addc_u32 s73, s73, 0
	s_add_u32 s74, s74, s12
	s_addc_u32 s75, s75, 0
	s_add_u32 s76, s76, 0x2b234000
	s_addc_u32 s77, s77, 0
	s_add_u32 s56, s14, 0x0
	s_addc_u32 s57, s15, 0
	s_add_u32 s58, s14, 0x10000
	s_addc_u32 s59, s15, 0
	s_add_u32 s60, s14, 0x20000
	s_addc_u32 s61, s15, 0
	s_add_u32 s62, s14, 0x30000
	s_addc_u32 s63, s15, 0
	s_add_u32 s64, s14, 0x80000
	s_addc_u32 s65, s15, 0
	s_add_u32 s66, s14, 0x90000
	s_addc_u32 s67, s15, 0
	s_add_u32 s68, s14, 0xa0000
	s_addc_u32 s69, s15, 0
	s_add_u32 s70, s14, 0xb0000
	s_addc_u32 s71, s15, 0
	s_nop 1
	global_load_dwordx2 v[146:147], v141, s[76:77] offset:0
	global_load_dwordx2 v[148:149], v141, s[76:77] offset:128
	global_load_dwordx4 v[154:157], v144, s[72:73]
	global_load_dwordx4 v[174:177], v144, s[74:75]
	global_load_dwordx4 v[162:165], v144, s[72:73] offset:64
	global_load_dwordx4 v[178:181], v144, s[74:75] offset:64
	global_load_dwordx4 v[166:169], v144, s[72:73] offset:512
	global_load_dwordx4 v[186:189], v144, s[74:75] offset:512
	global_load_dwordx4 v[170:173], v144, s[72:73] offset:576
	global_load_dwordx4 v[190:193], v144, s[74:75] offset:576
	global_load_dwordx4 v[194:197], v140, s[56:57]
	global_load_dwordx4 v[198:201], v140, s[56:57] offset:64
	global_load_dwordx4 v[204:207], v140, s[56:57] offset:512
	global_load_dwordx4 v[208:211], v140, s[56:57] offset:576
	global_load_dwordx4 v[212:215], v140, s[58:59]
	global_load_dwordx4 v[216:219], v140, s[58:59] offset:64
	global_load_dwordx4 v[220:223], v140, s[58:59] offset:512
	global_load_dwordx4 v[224:227], v140, s[58:59] offset:576
	global_load_dwordx4 v[228:231], v140, s[60:61]
	global_load_dwordx4 v[232:235], v140, s[60:61] offset:64
	global_load_dwordx4 v[236:239], v140, s[60:61] offset:512
	global_load_dwordx4 v[240:243], v140, s[60:61] offset:576
	global_load_dwordx4 v[244:247], v140, s[62:63]
	s_waitcnt vmcnt(12)
; DI bf16x4 pack4(float a, float b, float c, float d) { u32x2v u; u.x = pk2(a, b); u.y = pk2(c, d); return __builtin_bit_cast(bf16x4, u); }
; DI void ln_row_wave(const float* src, const float* g, const float* b, float* d32, bf16_t* db, int lane) {
;     ...
;   for (int i = 0; i < 4; ++i) {
;     float4 gg = reinterpret_cast<const float4*>(g)[lane + 64 * i], bb = reinterpret_cast<const float4*>(b)[lane + 64 * i];
;     float4 o;
;     o.x = (v[i].x - mu) * rstd * gg.x + bb.x; o.y = (v[i].y - mu) * rstd * gg.y + bb.y;
;     o.z = (v[i].z - mu) * rstd * gg.z + bb.z; o.w = (v[i].w - mu) * rstd * gg.w + bb.w;
;   DI void operator()(const f32x4 (&acc)[2][2][4][2], const pg8::Unit& u, int wr, int wc, int fr, int fq) const {
;     bf16_t* MERGED = (reinterpret_cast<bf16_t*>(p.ws + OFF_GA));
; #pragma unroll
;     for (int ai = 0; ai < 2; ++ai)
; #pragma unroll
;       for (int m = 0; m < 4; ++m) {
;         const int row = u.pm * 256 + 128 * ai + 64 * wr + 16 * m + fr;
; #pragma unroll
;         for (int bj = 0; bj < 2; ++bj)
; #pragma unroll
;           for (int n = 0; n < 2; ++n) {
;             const size_t idx = (size_t)row * 1024 + u.pn * 256 + 128 * bj + 32 * wc + 16 * n + 4 * fq;
;             const f32x4 a = acc[ai][bj][m][n];
;             if (MODE == 0) {
;               const unsigned g = *reinterpret_cast<const unsigned*>(reinterpret_cast<const unsigned char*>(p.ws + OFF_RB) + idx);
;               const float k = 1.f / 255.f;
;               st4(MERGED + idx, pack4((float)(g & 255u) * k * a[0], (float)((g >> 8) & 255u) * k * a[1], (float)((g >> 16) & 255u) * k * a[2], (float)(g >> 24) * k * a[3]));
;             } else {
;               f32x4 x = *reinterpret_cast<const f32x4*>(p.out + idx);
;               x = x * ALPHA + a;
;               *reinterpret_cast<f32x4*>(p.out + idx) = x;
;             }
	v_pk_add_f32 v[194:195], v[194:195], v[146:147] op_sel_hi:[1,0] neg_lo:[0,1] neg_hi:[0,1]
	v_pk_add_f32 v[196:197], v[196:197], v[146:147] op_sel_hi:[1,0] neg_lo:[0,1] neg_hi:[0,1]
	v_pk_mul_f32 v[194:195], v[194:195], v[146:147] op_sel:[0,1] op_sel_hi:[1,1]
	v_pk_mul_f32 v[196:197], v[196:197], v[146:147] op_sel:[0,1] op_sel_hi:[1,1]
	v_pk_fma_f32 v[194:195], v[194:195], v[154:155], v[174:175]
	v_pk_fma_f32 v[196:197], v[196:197], v[156:157], v[176:177]
	v_pk_fma_f32 v[130:131], v[194:195], s[16:17], v[130:131] op_sel_hi:[1,0,1]
	v_pk_fma_f32 v[132:133], v[196:197], s[16:17], v[132:133] op_sel_hi:[1,0,1]
	global_store_dwordx4 v140, v[130:133], s[56:57]
	global_load_dwordx4 v[194:197], v140, s[62:63] offset:64
	s_waitcnt vmcnt(13)
	v_pk_add_f32 v[198:199], v[198:199], v[146:147] op_sel_hi:[1,0] neg_lo:[0,1] neg_hi:[0,1]
	v_pk_add_f32 v[200:201], v[200:201], v[146:147] op_sel_hi:[1,0] neg_lo:[0,1] neg_hi:[0,1]
	v_pk_mul_f32 v[198:199], v[198:199], v[146:147] op_sel:[0,1] op_sel_hi:[1,1]
	v_pk_mul_f32 v[200:201], v[200:201], v[146:147] op_sel:[0,1] op_sel_hi:[1,1]
	v_pk_fma_f32 v[198:199], v[198:199], v[162:163], v[178:179]
	v_pk_fma_f32 v[200:201], v[200:201], v[164:165], v[180:181]
	v_pk_fma_f32 v[126:127], v[198:199], s[16:17], v[126:127] op_sel_hi:[1,0,1]
	v_pk_fma_f32 v[128:129], v[200:201], s[16:17], v[128:129] op_sel_hi:[1,0,1]
	global_store_dwordx4 v140, v[126:129], s[56:57] offset:64
	global_load_dwordx4 v[198:201], v140, s[62:63] offset:512
	s_waitcnt vmcnt(14)
	v_pk_add_f32 v[204:205], v[204:205], v[146:147] op_sel_hi:[1,0] neg_lo:[0,1] neg_hi:[0,1]
	v_pk_add_f32 v[206:207], v[206:207], v[146:147] op_sel_hi:[1,0] neg_lo:[0,1] neg_hi:[0,1]
	v_pk_mul_f32 v[204:205], v[204:205], v[146:147] op_sel:[0,1] op_sel_hi:[1,1]
	v_pk_mul_f32 v[206:207], v[206:207], v[146:147] op_sel:[0,1] op_sel_hi:[1,1]
	v_pk_fma_f32 v[204:205], v[204:205], v[166:167], v[186:187]
	v_pk_fma_f32 v[206:207], v[206:207], v[168:169], v[188:189]
	v_pk_fma_f32 v[122:123], v[204:205], s[16:17], v[122:123] op_sel_hi:[1,0,1]
	v_pk_fma_f32 v[124:125], v[206:207], s[16:17], v[124:125] op_sel_hi:[1,0,1]
	global_store_dwordx4 v140, v[122:125], s[56:57] offset:512
	global_load_dwordx4 v[204:207], v140, s[62:63] offset:576
	s_waitcnt vmcnt(15)
	v_pk_add_f32 v[208:209], v[208:209], v[146:147] op_sel_hi:[1,0] neg_lo:[0,1] neg_hi:[0,1]
	v_pk_add_f32 v[210:211], v[210:211], v[146:147] op_sel_hi:[1,0] neg_lo:[0,1] neg_hi:[0,1]
	v_pk_mul_f32 v[208:209], v[208:209], v[146:147] op_sel:[0,1] op_sel_hi:[1,1]
	v_pk_mul_f32 v[210:211], v[210:211], v[146:147] op_sel:[0,1] op_sel_hi:[1,1]
	v_pk_fma_f32 v[208:209], v[208:209], v[170:171], v[190:191]
	v_pk_fma_f32 v[210:211], v[210:211], v[172:173], v[192:193]
	v_pk_fma_f32 v[118:119], v[208:209], s[16:17], v[118:119] op_sel_hi:[1,0,1]
	v_pk_fma_f32 v[120:121], v[210:211], s[16:17], v[120:121] op_sel_hi:[1,0,1]
	global_store_dwordx4 v140, v[118:121], s[56:57] offset:576
	global_load_dwordx4 v[208:211], v140, s[64:65]
	global_load_dwordx2 v[146:147], v141, s[76:77] offset:256
	s_waitcnt vmcnt(17)
	v_pk_add_f32 v[212:213], v[212:213], v[148:149] op_sel_hi:[1,0] neg_lo:[0,1] neg_hi:[0,1]
	v_pk_add_f32 v[214:215], v[214:215], v[148:149] op_sel_hi:[1,0] neg_lo:[0,1] neg_hi:[0,1]
	v_pk_mul_f32 v[212:213], v[212:213], v[148:149] op_sel:[0,1] op_sel_hi:[1,1]
	v_pk_mul_f32 v[214:215], v[214:215], v[148:149] op_sel:[0,1] op_sel_hi:[1,1]
	v_pk_fma_f32 v[212:213], v[212:213], v[154:155], v[174:175]
	v_pk_fma_f32 v[214:215], v[214:215], v[156:157], v[176:177]
	v_pk_fma_f32 v[114:115], v[212:213], s[16:17], v[114:115] op_sel_hi:[1,0,1]
	v_pk_fma_f32 v[116:117], v[214:215], s[16:17], v[116:117] op_sel_hi:[1,0,1]
	global_store_dwordx4 v140, v[114:117], s[58:59]
	global_load_dwordx4 v[212:215], v140, s[64:65] offset:64
	s_waitcnt vmcnt(18)
	v_pk_add_f32 v[216:217], v[216:217], v[148:149] op_sel_hi:[1,0] neg_lo:[0,1] neg_hi:[0,1]
	v_pk_add_f32 v[218:219], v[218:219], v[148:149] op_sel_hi:[1,0] neg_lo:[0,1] neg_hi:[0,1]
	v_pk_mul_f32 v[216:217], v[216:217], v[148:149] op_sel:[0,1] op_sel_hi:[1,1]
	v_pk_mul_f32 v[218:219], v[218:219], v[148:149] op_sel:[0,1] op_sel_hi:[1,1]
	v_pk_fma_f32 v[216:217], v[216:217], v[162:163], v[178:179]
	v_pk_fma_f32 v[218:219], v[218:219], v[164:165], v[180:181]
	v_pk_fma_f32 v[110:111], v[216:217], s[16:17], v[110:111] op_sel_hi:[1,0,1]
	v_pk_fma_f32 v[112:113], v[218:219], s[16:17], v[112:113] op_sel_hi:[1,0,1]
	global_store_dwordx4 v140, v[110:113], s[58:59] offset:64
	global_load_dwordx4 v[216:219], v140, s[64:65] offset:512
	s_waitcnt vmcnt(19)
	v_pk_add_f32 v[220:221], v[220:221], v[148:149] op_sel_hi:[1,0] neg_lo:[0,1] neg_hi:[0,1]
	v_pk_add_f32 v[222:223], v[222:223], v[148:149] op_sel_hi:[1,0] neg_lo:[0,1] neg_hi:[0,1]
	v_pk_mul_f32 v[220:221], v[220:221], v[148:149] op_sel:[0,1] op_sel_hi:[1,1]
	v_pk_mul_f32 v[222:223], v[222:223], v[148:149] op_sel:[0,1] op_sel_hi:[1,1]
	v_pk_fma_f32 v[220:221], v[220:221], v[166:167], v[186:187]
	v_pk_fma_f32 v[222:223], v[222:223], v[168:169], v[188:189]
	v_pk_fma_f32 v[106:107], v[220:221], s[16:17], v[106:107] op_sel_hi:[1,0,1]
	v_pk_fma_f32 v[108:109], v[222:223], s[16:17], v[108:109] op_sel_hi:[1,0,1]
	global_store_dwordx4 v140, v[106:109], s[58:59] offset:512
	global_load_dwordx4 v[220:223], v140, s[64:65] offset:576
	s_waitcnt vmcnt(20)
; DI bf16x4 pack4(float a, float b, float c, float d) { u32x2v u; u.x = pk2(a, b); u.y = pk2(c, d); return __builtin_bit_cast(bf16x4, u); }
; DI void ln_row_wave(const float* src, const float* g, const float* b, float* d32, bf16_t* db, int lane) {
;     ...
;   for (int i = 0; i < 4; ++i) {
;     float4 gg = reinterpret_cast<const float4*>(g)[lane + 64 * i], bb = reinterpret_cast<const float4*>(b)[lane + 64 * i];
;     float4 o;
;     o.x = (v[i].x - mu) * rstd * gg.x + bb.x; o.y = (v[i].y - mu) * rstd * gg.y + bb.y;
;     o.z = (v[i].z - mu) * rstd * gg.z + bb.z; o.w = (v[i].w - mu) * rstd * gg.w + bb.w;
;   DI void operator()(const f32x4 (&acc)[2][2][4][2], const pg8::Unit& u, int wr, int wc, int fr, int fq) const {
;     bf16_t* MERGED = (reinterpret_cast<bf16_t*>(p.ws + OFF_GA));
; #pragma unroll
;     for (int ai = 0; ai < 2; ++ai)
; #pragma unroll
;       for (int m = 0; m < 4; ++m) {
;         const int row = u.pm * 256 + 128 * ai + 64 * wr + 16 * m + fr;
; #pragma unroll
;         for (int bj = 0; bj < 2; ++bj)
; #pragma unroll
;           for (int n = 0; n < 2; ++n) {
;             const size_t idx = (size_t)row * 1024 + u.pn * 256 + 128 * bj + 32 * wc + 16 * n + 4 * fq;
;             const f32x4 a = acc[ai][bj][m][n];
;             if (MODE == 0) {
;               const unsigned g = *reinterpret_cast<const unsigned*>(reinterpret_cast<const unsigned char*>(p.ws + OFF_RB) + idx);
;               const float k = 1.f / 255.f;
;               st4(MERGED + idx, pack4((float)(g & 255u) * k * a[0], (float)((g >> 8) & 255u) * k * a[1], (float)((g >> 16) & 255u) * k * a[2], (float)(g >> 24) * k * a[3]));
;             } else {
;               f32x4 x = *reinterpret_cast<const f32x4*>(p.out + idx);
;               x = x * ALPHA + a;
;               *reinterpret_cast<f32x4*>(p.out + idx) = x;
;             }
	v_pk_add_f32 v[224:225], v[224:225], v[148:149] op_sel_hi:[1,0] neg_lo:[0,1] neg_hi:[0,1]
	v_pk_add_f32 v[226:227], v[226:227], v[148:149] op_sel_hi:[1,0] neg_lo:[0,1] neg_hi:[0,1]
	v_pk_mul_f32 v[224:225], v[224:225], v[148:149] op_sel:[0,1] op_sel_hi:[1,1]
	v_pk_mul_f32 v[226:227], v[226:227], v[148:149] op_sel:[0,1] op_sel_hi:[1,1]
	v_pk_fma_f32 v[224:225], v[224:225], v[170:171], v[190:191]
	v_pk_fma_f32 v[226:227], v[226:227], v[172:173], v[192:193]
	v_pk_fma_f32 v[102:103], v[224:225], s[16:17], v[102:103] op_sel_hi:[1,0,1]
	v_pk_fma_f32 v[104:105], v[226:227], s[16:17], v[104:105] op_sel_hi:[1,0,1]
	global_store_dwordx4 v140, v[102:105], s[58:59] offset:576
	global_load_dwordx4 v[224:227], v140, s[66:67]
	global_load_dwordx2 v[148:149], v141, s[76:77] offset:384
	s_waitcnt vmcnt(9)
	v_pk_add_f32 v[228:229], v[228:229], v[146:147] op_sel_hi:[1,0] neg_lo:[0,1] neg_hi:[0,1]
	v_pk_add_f32 v[230:231], v[230:231], v[146:147] op_sel_hi:[1,0] neg_lo:[0,1] neg_hi:[0,1]
	v_pk_mul_f32 v[228:229], v[228:229], v[146:147] op_sel:[0,1] op_sel_hi:[1,1]
	v_pk_mul_f32 v[230:231], v[230:231], v[146:147] op_sel:[0,1] op_sel_hi:[1,1]
	v_pk_fma_f32 v[228:229], v[228:229], v[154:155], v[174:175]
	v_pk_fma_f32 v[230:231], v[230:231], v[156:157], v[176:177]
	v_pk_fma_f32 v[98:99], v[228:229], s[16:17], v[98:99] op_sel_hi:[1,0,1]
	v_pk_fma_f32 v[100:101], v[230:231], s[16:17], v[100:101] op_sel_hi:[1,0,1]
	global_store_dwordx4 v140, v[98:101], s[60:61]
	global_load_dwordx4 v[228:231], v140, s[66:67] offset:64
	s_waitcnt vmcnt(11)
	v_pk_add_f32 v[232:233], v[232:233], v[146:147] op_sel_hi:[1,0] neg_lo:[0,1] neg_hi:[0,1]
	v_pk_add_f32 v[234:235], v[234:235], v[146:147] op_sel_hi:[1,0] neg_lo:[0,1] neg_hi:[0,1]
	v_pk_mul_f32 v[232:233], v[232:233], v[146:147] op_sel:[0,1] op_sel_hi:[1,1]
	v_pk_mul_f32 v[234:235], v[234:235], v[146:147] op_sel:[0,1] op_sel_hi:[1,1]
	v_pk_fma_f32 v[232:233], v[232:233], v[162:163], v[178:179]
	v_pk_fma_f32 v[234:235], v[234:235], v[164:165], v[180:181]
	v_pk_fma_f32 v[94:95], v[232:233], s[16:17], v[94:95] op_sel_hi:[1,0,1]
	v_pk_fma_f32 v[96:97], v[234:235], s[16:17], v[96:97] op_sel_hi:[1,0,1]
	global_store_dwordx4 v140, v[94:97], s[60:61] offset:64
	global_load_dwordx4 v[232:235], v140, s[66:67] offset:512
	s_waitcnt vmcnt(13)
	v_pk_add_f32 v[236:237], v[236:237], v[146:147] op_sel_hi:[1,0] neg_lo:[0,1] neg_hi:[0,1]
	v_pk_add_f32 v[238:239], v[238:239], v[146:147] op_sel_hi:[1,0] neg_lo:[0,1] neg_hi:[0,1]
	v_pk_mul_f32 v[236:237], v[236:237], v[146:147] op_sel:[0,1] op_sel_hi:[1,1]
	v_pk_mul_f32 v[238:239], v[238:239], v[146:147] op_sel:[0,1] op_sel_hi:[1,1]
	v_pk_fma_f32 v[236:237], v[236:237], v[166:167], v[186:187]
	v_pk_fma_f32 v[238:239], v[238:239], v[168:169], v[188:189]
	v_pk_fma_f32 v[90:91], v[236:237], s[16:17], v[90:91] op_sel_hi:[1,0,1]
	v_pk_fma_f32 v[92:93], v[238:239], s[16:17], v[92:93] op_sel_hi:[1,0,1]
	global_store_dwordx4 v140, v[90:93], s[60:61] offset:512
	global_load_dwordx4 v[236:239], v140, s[66:67] offset:576
	s_waitcnt vmcnt(15)
	v_pk_add_f32 v[240:241], v[240:241], v[146:147] op_sel_hi:[1,0] neg_lo:[0,1] neg_hi:[0,1]
	v_pk_add_f32 v[242:243], v[242:243], v[146:147] op_sel_hi:[1,0] neg_lo:[0,1] neg_hi:[0,1]
	v_pk_mul_f32 v[240:241], v[240:241], v[146:147] op_sel:[0,1] op_sel_hi:[1,1]
	v_pk_mul_f32 v[242:243], v[242:243], v[146:147] op_sel:[0,1] op_sel_hi:[1,1]
	v_pk_fma_f32 v[240:241], v[240:241], v[170:171], v[190:191]
	v_pk_fma_f32 v[242:243], v[242:243], v[172:173], v[192:193]
	v_pk_fma_f32 v[86:87], v[240:241], s[16:17], v[86:87] op_sel_hi:[1,0,1]
	v_pk_fma_f32 v[88:89], v[242:243], s[16:17], v[88:89] op_sel_hi:[1,0,1]
	global_store_dwordx4 v140, v[86:89], s[60:61] offset:576
	global_load_dwordx4 v[240:243], v140, s[68:69]
	global_load_dwordx2 v[146:147], v141, s[76:77] offset:1024
	s_waitcnt vmcnt(9)
	v_pk_add_f32 v[244:245], v[244:245], v[148:149] op_sel_hi:[1,0] neg_lo:[0,1] neg_hi:[0,1]
	v_pk_add_f32 v[246:247], v[246:247], v[148:149] op_sel_hi:[1,0] neg_lo:[0,1] neg_hi:[0,1]
	v_pk_mul_f32 v[244:245], v[244:245], v[148:149] op_sel:[0,1] op_sel_hi:[1,1]
	v_pk_mul_f32 v[246:247], v[246:247], v[148:149] op_sel:[0,1] op_sel_hi:[1,1]
	v_pk_fma_f32 v[244:245], v[244:245], v[154:155], v[174:175]
	v_pk_fma_f32 v[246:247], v[246:247], v[156:157], v[176:177]
	v_pk_fma_f32 v[82:83], v[244:245], s[16:17], v[82:83] op_sel_hi:[1,0,1]
	v_pk_fma_f32 v[84:85], v[246:247], s[16:17], v[84:85] op_sel_hi:[1,0,1]
	global_store_dwordx4 v140, v[82:85], s[62:63]
	global_load_dwordx4 v[244:247], v140, s[68:69] offset:64
	s_waitcnt vmcnt(11)
	v_pk_add_f32 v[194:195], v[194:195], v[148:149] op_sel_hi:[1,0] neg_lo:[0,1] neg_hi:[0,1]
	v_pk_add_f32 v[196:197], v[196:197], v[148:149] op_sel_hi:[1,0] neg_lo:[0,1] neg_hi:[0,1]
	v_pk_mul_f32 v[194:195], v[194:195], v[148:149] op_sel:[0,1] op_sel_hi:[1,1]
	v_pk_mul_f32 v[196:197], v[196:197], v[148:149] op_sel:[0,1] op_sel_hi:[1,1]
	v_pk_fma_f32 v[194:195], v[194:195], v[162:163], v[178:179]
	v_pk_fma_f32 v[196:197], v[196:197], v[164:165], v[180:181]
	v_pk_fma_f32 v[78:79], v[194:195], s[16:17], v[78:79] op_sel_hi:[1,0,1]
	v_pk_fma_f32 v[80:81], v[196:197], s[16:17], v[80:81] op_sel_hi:[1,0,1]
	global_store_dwordx4 v140, v[78:81], s[62:63] offset:64
	global_load_dwordx4 v[194:197], v140, s[68:69] offset:512
	s_waitcnt vmcnt(13)
; DI bf16x4 pack4(float a, float b, float c, float d) { u32x2v u; u.x = pk2(a, b); u.y = pk2(c, d); return __builtin_bit_cast(bf16x4, u); }
; DI void ln_row_wave(const float* src, const float* g, const float* b, float* d32, bf16_t* db, int lane) {
;     ...
;   for (int i = 0; i < 4; ++i) {
;     float4 gg = reinterpret_cast<const float4*>(g)[lane + 64 * i], bb = reinterpret_cast<const float4*>(b)[lane + 64 * i];
;     float4 o;
;     o.x = (v[i].x - mu) * rstd * gg.x + bb.x; o.y = (v[i].y - mu) * rstd * gg.y + bb.y;
;     o.z = (v[i].z - mu) * rstd * gg.z + bb.z; o.w = (v[i].w - mu) * rstd * gg.w + bb.w;
;   DI void operator()(const f32x4 (&acc)[2][2][4][2], const pg8::Unit& u, int wr, int wc, int fr, int fq) const {
;     bf16_t* MERGED = (reinterpret_cast<bf16_t*>(p.ws + OFF_GA));
; #pragma unroll
;     for (int ai = 0; ai < 2; ++ai)
; #pragma unroll
;       for (int m = 0; m < 4; ++m) {
;         const int row = u.pm * 256 + 128 * ai + 64 * wr + 16 * m + fr;
; #pragma unroll
;         for (int bj = 0; bj < 2; ++bj)
; #pragma unroll
;           for (int n = 0; n < 2; ++n) {
;             const size_t idx = (size_t)row * 1024 + u.pn * 256 + 128 * bj + 32 * wc + 16 * n + 4 * fq;
;             const f32x4 a = acc[ai][bj][m][n];
;             if (MODE == 0) {
;               const unsigned g = *reinterpret_cast<const unsigned*>(reinterpret_cast<const unsigned char*>(p.ws + OFF_RB) + idx);
;               const float k = 1.f / 255.f;
;               st4(MERGED + idx, pack4((float)(g & 255u) * k * a[0], (float)((g >> 8) & 255u) * k * a[1], (float)((g >> 16) & 255u) * k * a[2], (float)(g >> 24) * k * a[3]));
;             } else {
;               f32x4 x = *reinterpret_cast<const f32x4*>(p.out + idx);
;               x = x * ALPHA + a;
;               *reinterpret_cast<f32x4*>(p.out + idx) = x;
;             }
	v_pk_add_f32 v[198:199], v[198:199], v[148:149] op_sel_hi:[1,0] neg_lo:[0,1] neg_hi:[0,1]
	v_pk_add_f32 v[200:201], v[200:201], v[148:149] op_sel_hi:[1,0] neg_lo:[0,1] neg_hi:[0,1]
	v_pk_mul_f32 v[198:199], v[198:199], v[148:149] op_sel:[0,1] op_sel_hi:[1,1]
	v_pk_mul_f32 v[200:201], v[200:201], v[148:149] op_sel:[0,1] op_sel_hi:[1,1]
	v_pk_fma_f32 v[198:199], v[198:199], v[166:167], v[186:187]
	v_pk_fma_f32 v[200:201], v[200:201], v[168:169], v[188:189]
	v_pk_fma_f32 v[74:75], v[198:199], s[16:17], v[74:75] op_sel_hi:[1,0,1]
	v_pk_fma_f32 v[76:77], v[200:201], s[16:17], v[76:77] op_sel_hi:[1,0,1]
	global_store_dwordx4 v140, v[74:77], s[62:63] offset:512
	global_load_dwordx4 v[198:201], v140, s[68:69] offset:576
	s_waitcnt vmcnt(15)
	v_pk_add_f32 v[204:205], v[204:205], v[148:149] op_sel_hi:[1,0] neg_lo:[0,1] neg_hi:[0,1]
	v_pk_add_f32 v[206:207], v[206:207], v[148:149] op_sel_hi:[1,0] neg_lo:[0,1] neg_hi:[0,1]
	v_pk_mul_f32 v[204:205], v[204:205], v[148:149] op_sel:[0,1] op_sel_hi:[1,1]
	v_pk_mul_f32 v[206:207], v[206:207], v[148:149] op_sel:[0,1] op_sel_hi:[1,1]
	v_pk_fma_f32 v[204:205], v[204:205], v[170:171], v[190:191]
	v_pk_fma_f32 v[206:207], v[206:207], v[172:173], v[192:193]
	v_pk_fma_f32 v[70:71], v[204:205], s[16:17], v[70:71] op_sel_hi:[1,0,1]
	v_pk_fma_f32 v[72:73], v[206:207], s[16:17], v[72:73] op_sel_hi:[1,0,1]
	global_store_dwordx4 v140, v[70:73], s[62:63] offset:576
	global_load_dwordx4 v[204:207], v140, s[70:71]
	global_load_dwordx2 v[148:149], v141, s[76:77] offset:1152
	s_waitcnt vmcnt(9)
	v_pk_add_f32 v[208:209], v[208:209], v[146:147] op_sel_hi:[1,0] neg_lo:[0,1] neg_hi:[0,1]
	v_pk_add_f32 v[210:211], v[210:211], v[146:147] op_sel_hi:[1,0] neg_lo:[0,1] neg_hi:[0,1]
	v_pk_mul_f32 v[208:209], v[208:209], v[146:147] op_sel:[0,1] op_sel_hi:[1,1]
	v_pk_mul_f32 v[210:211], v[210:211], v[146:147] op_sel:[0,1] op_sel_hi:[1,1]
	v_pk_fma_f32 v[208:209], v[208:209], v[154:155], v[174:175]
	v_pk_fma_f32 v[210:211], v[210:211], v[156:157], v[176:177]
	v_pk_fma_f32 v[66:67], v[208:209], s[16:17], v[66:67] op_sel_hi:[1,0,1]
	v_pk_fma_f32 v[68:69], v[210:211], s[16:17], v[68:69] op_sel_hi:[1,0,1]
	global_store_dwordx4 v140, v[66:69], s[64:65]
	global_load_dwordx4 v[208:211], v140, s[70:71] offset:64
	s_waitcnt vmcnt(11)
	v_pk_add_f32 v[212:213], v[212:213], v[146:147] op_sel_hi:[1,0] neg_lo:[0,1] neg_hi:[0,1]
	v_pk_add_f32 v[214:215], v[214:215], v[146:147] op_sel_hi:[1,0] neg_lo:[0,1] neg_hi:[0,1]
	v_pk_mul_f32 v[212:213], v[212:213], v[146:147] op_sel:[0,1] op_sel_hi:[1,1]
	v_pk_mul_f32 v[214:215], v[214:215], v[146:147] op_sel:[0,1] op_sel_hi:[1,1]
	v_pk_fma_f32 v[212:213], v[212:213], v[162:163], v[178:179]
	v_pk_fma_f32 v[214:215], v[214:215], v[164:165], v[180:181]
	v_pk_fma_f32 v[62:63], v[212:213], s[16:17], v[62:63] op_sel_hi:[1,0,1]
	v_pk_fma_f32 v[64:65], v[214:215], s[16:17], v[64:65] op_sel_hi:[1,0,1]
	global_store_dwordx4 v140, v[62:65], s[64:65] offset:64
	global_load_dwordx4 v[212:215], v140, s[70:71] offset:512
	s_waitcnt vmcnt(13)
	v_pk_add_f32 v[216:217], v[216:217], v[146:147] op_sel_hi:[1,0] neg_lo:[0,1] neg_hi:[0,1]
	v_pk_add_f32 v[218:219], v[218:219], v[146:147] op_sel_hi:[1,0] neg_lo:[0,1] neg_hi:[0,1]
	v_pk_mul_f32 v[216:217], v[216:217], v[146:147] op_sel:[0,1] op_sel_hi:[1,1]
	v_pk_mul_f32 v[218:219], v[218:219], v[146:147] op_sel:[0,1] op_sel_hi:[1,1]
	v_pk_fma_f32 v[216:217], v[216:217], v[166:167], v[186:187]
	v_pk_fma_f32 v[218:219], v[218:219], v[168:169], v[188:189]
	v_pk_fma_f32 v[58:59], v[216:217], s[16:17], v[58:59] op_sel_hi:[1,0,1]
	v_pk_fma_f32 v[60:61], v[218:219], s[16:17], v[60:61] op_sel_hi:[1,0,1]
	global_store_dwordx4 v140, v[58:61], s[64:65] offset:512
	global_load_dwordx4 v[216:219], v140, s[70:71] offset:576
	s_waitcnt vmcnt(15)
	v_pk_add_f32 v[220:221], v[220:221], v[146:147] op_sel_hi:[1,0] neg_lo:[0,1] neg_hi:[0,1]
	v_pk_add_f32 v[222:223], v[222:223], v[146:147] op_sel_hi:[1,0] neg_lo:[0,1] neg_hi:[0,1]
	v_pk_mul_f32 v[220:221], v[220:221], v[146:147] op_sel:[0,1] op_sel_hi:[1,1]
	v_pk_mul_f32 v[222:223], v[222:223], v[146:147] op_sel:[0,1] op_sel_hi:[1,1]
	v_pk_fma_f32 v[220:221], v[220:221], v[170:171], v[190:191]
	v_pk_fma_f32 v[222:223], v[222:223], v[172:173], v[192:193]
	v_pk_fma_f32 v[54:55], v[220:221], s[16:17], v[54:55] op_sel_hi:[1,0,1]
	v_pk_fma_f32 v[56:57], v[222:223], s[16:17], v[56:57] op_sel_hi:[1,0,1]
	global_store_dwordx4 v140, v[54:57], s[64:65] offset:576
	global_load_dwordx2 v[146:147], v141, s[76:77] offset:1280
	s_waitcnt vmcnt(8)
	v_pk_add_f32 v[224:225], v[224:225], v[148:149] op_sel_hi:[1,0] neg_lo:[0,1] neg_hi:[0,1]
	v_pk_add_f32 v[226:227], v[226:227], v[148:149] op_sel_hi:[1,0] neg_lo:[0,1] neg_hi:[0,1]
	v_pk_mul_f32 v[224:225], v[224:225], v[148:149] op_sel:[0,1] op_sel_hi:[1,1]
	v_pk_mul_f32 v[226:227], v[226:227], v[148:149] op_sel:[0,1] op_sel_hi:[1,1]
	v_pk_fma_f32 v[224:225], v[224:225], v[154:155], v[174:175]
	v_pk_fma_f32 v[226:227], v[226:227], v[156:157], v[176:177]
	v_pk_fma_f32 v[50:51], v[224:225], s[16:17], v[50:51] op_sel_hi:[1,0,1]
	v_pk_fma_f32 v[52:53], v[226:227], s[16:17], v[52:53] op_sel_hi:[1,0,1]
	global_store_dwordx4 v140, v[50:53], s[66:67]
	s_waitcnt vmcnt(9)
	v_pk_add_f32 v[228:229], v[228:229], v[148:149] op_sel_hi:[1,0] neg_lo:[0,1] neg_hi:[0,1]
	v_pk_add_f32 v[230:231], v[230:231], v[148:149] op_sel_hi:[1,0] neg_lo:[0,1] neg_hi:[0,1]
	v_pk_mul_f32 v[228:229], v[228:229], v[148:149] op_sel:[0,1] op_sel_hi:[1,1]
	v_pk_mul_f32 v[230:231], v[230:231], v[148:149] op_sel:[0,1] op_sel_hi:[1,1]
	v_pk_fma_f32 v[228:229], v[228:229], v[162:163], v[178:179]
	v_pk_fma_f32 v[230:231], v[230:231], v[164:165], v[180:181]
	v_pk_fma_f32 v[46:47], v[228:229], s[16:17], v[46:47] op_sel_hi:[1,0,1]
	v_pk_fma_f32 v[48:49], v[230:231], s[16:17], v[48:49] op_sel_hi:[1,0,1]
	global_store_dwordx4 v140, v[46:49], s[66:67] offset:64
	s_waitcnt vmcnt(10)
; DI bf16x4 pack4(float a, float b, float c, float d) { u32x2v u; u.x = pk2(a, b); u.y = pk2(c, d); return __builtin_bit_cast(bf16x4, u); }
; DI void ln_row_wave(const float* src, const float* g, const float* b, float* d32, bf16_t* db, int lane) {
;     ...
;   for (int i = 0; i < 4; ++i) {
;     float4 gg = reinterpret_cast<const float4*>(g)[lane + 64 * i], bb = reinterpret_cast<const float4*>(b)[lane + 64 * i];
;     float4 o;
;     o.x = (v[i].x - mu) * rstd * gg.x + bb.x; o.y = (v[i].y - mu) * rstd * gg.y + bb.y;
;     o.z = (v[i].z - mu) * rstd * gg.z + bb.z; o.w = (v[i].w - mu) * rstd * gg.w + bb.w;
;   DI void operator()(const f32x4 (&acc)[2][2][4][2], const pg8::Unit& u, int wr, int wc, int fr, int fq) const {
;     bf16_t* MERGED = (reinterpret_cast<bf16_t*>(p.ws + OFF_GA));
; #pragma unroll
;     for (int ai = 0; ai < 2; ++ai)
; #pragma unroll
;       for (int m = 0; m < 4; ++m) {
;         const int row = u.pm * 256 + 128 * ai + 64 * wr + 16 * m + fr;
; #pragma unroll
;         for (int bj = 0; bj < 2; ++bj)
; #pragma unroll
;           for (int n = 0; n < 2; ++n) {
;             const size_t idx = (size_t)row * 1024 + u.pn * 256 + 128 * bj + 32 * wc + 16 * n + 4 * fq;
;             const f32x4 a = acc[ai][bj][m][n];
;             if (MODE == 0) {
;               const unsigned g = *reinterpret_cast<const unsigned*>(reinterpret_cast<const unsigned char*>(p.ws + OFF_RB) + idx);
;               const float k = 1.f / 255.f;
;               st4(MERGED + idx, pack4((float)(g & 255u) * k * a[0], (float)((g >> 8) & 255u) * k * a[1], (float)((g >> 16) & 255u) * k * a[2], (float)(g >> 24) * k * a[3]));
;             } else {
;               f32x4 x = *reinterpret_cast<const f32x4*>(p.out + idx);
;               x = x * ALPHA + a;
;               *reinterpret_cast<f32x4*>(p.out + idx) = x;
;             }
	v_pk_add_f32 v[232:233], v[232:233], v[148:149] op_sel_hi:[1,0] neg_lo:[0,1] neg_hi:[0,1]
	v_pk_add_f32 v[234:235], v[234:235], v[148:149] op_sel_hi:[1,0] neg_lo:[0,1] neg_hi:[0,1]
	v_pk_mul_f32 v[232:233], v[232:233], v[148:149] op_sel:[0,1] op_sel_hi:[1,1]
	v_pk_mul_f32 v[234:235], v[234:235], v[148:149] op_sel:[0,1] op_sel_hi:[1,1]
	v_pk_fma_f32 v[232:233], v[232:233], v[166:167], v[186:187]
	v_pk_fma_f32 v[234:235], v[234:235], v[168:169], v[188:189]
	v_pk_fma_f32 v[42:43], v[232:233], s[16:17], v[42:43] op_sel_hi:[1,0,1]
	v_pk_fma_f32 v[44:45], v[234:235], s[16:17], v[44:45] op_sel_hi:[1,0,1]
	global_store_dwordx4 v140, v[42:45], s[66:67] offset:512
	s_waitcnt vmcnt(11)
	v_pk_add_f32 v[236:237], v[236:237], v[148:149] op_sel_hi:[1,0] neg_lo:[0,1] neg_hi:[0,1]
	v_pk_add_f32 v[238:239], v[238:239], v[148:149] op_sel_hi:[1,0] neg_lo:[0,1] neg_hi:[0,1]
	v_pk_mul_f32 v[236:237], v[236:237], v[148:149] op_sel:[0,1] op_sel_hi:[1,1]
	v_pk_mul_f32 v[238:239], v[238:239], v[148:149] op_sel:[0,1] op_sel_hi:[1,1]
	v_pk_fma_f32 v[236:237], v[236:237], v[170:171], v[190:191]
	v_pk_fma_f32 v[238:239], v[238:239], v[172:173], v[192:193]
	v_pk_fma_f32 v[38:39], v[236:237], s[16:17], v[38:39] op_sel_hi:[1,0,1]
	v_pk_fma_f32 v[40:41], v[238:239], s[16:17], v[40:41] op_sel_hi:[1,0,1]
	global_store_dwordx4 v140, v[38:41], s[66:67] offset:576
	global_load_dwordx2 v[148:149], v141, s[76:77] offset:1408
	s_waitcnt vmcnt(5)
	v_pk_add_f32 v[240:241], v[240:241], v[146:147] op_sel_hi:[1,0] neg_lo:[0,1] neg_hi:[0,1]
	v_pk_add_f32 v[242:243], v[242:243], v[146:147] op_sel_hi:[1,0] neg_lo:[0,1] neg_hi:[0,1]
	v_pk_mul_f32 v[240:241], v[240:241], v[146:147] op_sel:[0,1] op_sel_hi:[1,1]
	v_pk_mul_f32 v[242:243], v[242:243], v[146:147] op_sel:[0,1] op_sel_hi:[1,1]
	v_pk_fma_f32 v[240:241], v[240:241], v[154:155], v[174:175]
	v_pk_fma_f32 v[242:243], v[242:243], v[156:157], v[176:177]
	v_pk_fma_f32 v[34:35], v[240:241], s[16:17], v[34:35] op_sel_hi:[1,0,1]
	v_pk_fma_f32 v[36:37], v[242:243], s[16:17], v[36:37] op_sel_hi:[1,0,1]
	global_store_dwordx4 v140, v[34:37], s[68:69]
	s_waitcnt vmcnt(6)
	v_pk_add_f32 v[244:245], v[244:245], v[146:147] op_sel_hi:[1,0] neg_lo:[0,1] neg_hi:[0,1]
	v_pk_add_f32 v[246:247], v[246:247], v[146:147] op_sel_hi:[1,0] neg_lo:[0,1] neg_hi:[0,1]
	v_pk_mul_f32 v[244:245], v[244:245], v[146:147] op_sel:[0,1] op_sel_hi:[1,1]
	v_pk_mul_f32 v[246:247], v[246:247], v[146:147] op_sel:[0,1] op_sel_hi:[1,1]
	v_pk_fma_f32 v[244:245], v[244:245], v[162:163], v[178:179]
	v_pk_fma_f32 v[246:247], v[246:247], v[164:165], v[180:181]
	v_pk_fma_f32 v[30:31], v[244:245], s[16:17], v[30:31] op_sel_hi:[1,0,1]
	v_pk_fma_f32 v[32:33], v[246:247], s[16:17], v[32:33] op_sel_hi:[1,0,1]
	global_store_dwordx4 v140, v[30:33], s[68:69] offset:64
	s_waitcnt vmcnt(7)
	v_pk_add_f32 v[194:195], v[194:195], v[146:147] op_sel_hi:[1,0] neg_lo:[0,1] neg_hi:[0,1]
	v_pk_add_f32 v[196:197], v[196:197], v[146:147] op_sel_hi:[1,0] neg_lo:[0,1] neg_hi:[0,1]
	v_pk_mul_f32 v[194:195], v[194:195], v[146:147] op_sel:[0,1] op_sel_hi:[1,1]
	v_pk_mul_f32 v[196:197], v[196:197], v[146:147] op_sel:[0,1] op_sel_hi:[1,1]
	v_pk_fma_f32 v[194:195], v[194:195], v[166:167], v[186:187]
	v_pk_fma_f32 v[196:197], v[196:197], v[168:169], v[188:189]
	v_pk_fma_f32 v[26:27], v[194:195], s[16:17], v[26:27] op_sel_hi:[1,0,1]
	v_pk_fma_f32 v[28:29], v[196:197], s[16:17], v[28:29] op_sel_hi:[1,0,1]
	global_store_dwordx4 v140, v[26:29], s[68:69] offset:512
	s_waitcnt vmcnt(8)
	v_pk_add_f32 v[198:199], v[198:199], v[146:147] op_sel_hi:[1,0] neg_lo:[0,1] neg_hi:[0,1]
	v_pk_add_f32 v[200:201], v[200:201], v[146:147] op_sel_hi:[1,0] neg_lo:[0,1] neg_hi:[0,1]
	v_pk_mul_f32 v[198:199], v[198:199], v[146:147] op_sel:[0,1] op_sel_hi:[1,1]
	v_pk_mul_f32 v[200:201], v[200:201], v[146:147] op_sel:[0,1] op_sel_hi:[1,1]
	v_pk_fma_f32 v[198:199], v[198:199], v[170:171], v[190:191]
	v_pk_fma_f32 v[200:201], v[200:201], v[172:173], v[192:193]
	v_pk_fma_f32 v[22:23], v[198:199], s[16:17], v[22:23] op_sel_hi:[1,0,1]
	v_pk_fma_f32 v[24:25], v[200:201], s[16:17], v[24:25] op_sel_hi:[1,0,1]
	global_store_dwordx4 v140, v[22:25], s[68:69] offset:576
	s_waitcnt vmcnt(4)
	v_pk_add_f32 v[204:205], v[204:205], v[148:149] op_sel_hi:[1,0] neg_lo:[0,1] neg_hi:[0,1]
	v_pk_add_f32 v[206:207], v[206:207], v[148:149] op_sel_hi:[1,0] neg_lo:[0,1] neg_hi:[0,1]
	v_pk_mul_f32 v[204:205], v[204:205], v[148:149] op_sel:[0,1] op_sel_hi:[1,1]
	v_pk_mul_f32 v[206:207], v[206:207], v[148:149] op_sel:[0,1] op_sel_hi:[1,1]
	v_pk_fma_f32 v[204:205], v[204:205], v[154:155], v[174:175]
	v_pk_fma_f32 v[206:207], v[206:207], v[156:157], v[176:177]
	v_pk_fma_f32 v[12:13], v[204:205], s[16:17], v[12:13] op_sel_hi:[1,0,1]
	v_pk_fma_f32 v[14:15], v[206:207], s[16:17], v[14:15] op_sel_hi:[1,0,1]
	global_store_dwordx4 v140, v[12:15], s[70:71]
	s_waitcnt vmcnt(5)
	v_pk_add_f32 v[208:209], v[208:209], v[148:149] op_sel_hi:[1,0] neg_lo:[0,1] neg_hi:[0,1]
	v_pk_add_f32 v[210:211], v[210:211], v[148:149] op_sel_hi:[1,0] neg_lo:[0,1] neg_hi:[0,1]
	v_pk_mul_f32 v[208:209], v[208:209], v[148:149] op_sel:[0,1] op_sel_hi:[1,1]
	v_pk_mul_f32 v[210:211], v[210:211], v[148:149] op_sel:[0,1] op_sel_hi:[1,1]
	v_pk_fma_f32 v[208:209], v[208:209], v[162:163], v[178:179]
	v_pk_fma_f32 v[210:211], v[210:211], v[164:165], v[180:181]
	v_pk_fma_f32 v[8:9], v[208:209], s[16:17], v[8:9] op_sel_hi:[1,0,1]
	v_pk_fma_f32 v[10:11], v[210:211], s[16:17], v[10:11] op_sel_hi:[1,0,1]
	global_store_dwordx4 v140, v[8:11], s[70:71] offset:64
	s_waitcnt vmcnt(6)
	v_pk_add_f32 v[212:213], v[212:213], v[148:149] op_sel_hi:[1,0] neg_lo:[0,1] neg_hi:[0,1]
	v_pk_add_f32 v[214:215], v[214:215], v[148:149] op_sel_hi:[1,0] neg_lo:[0,1] neg_hi:[0,1]
	v_pk_mul_f32 v[212:213], v[212:213], v[148:149] op_sel:[0,1] op_sel_hi:[1,1]
	v_pk_mul_f32 v[214:215], v[214:215], v[148:149] op_sel:[0,1] op_sel_hi:[1,1]
	v_pk_fma_f32 v[212:213], v[212:213], v[166:167], v[186:187]
	v_pk_fma_f32 v[214:215], v[214:215], v[168:169], v[188:189]
	v_pk_fma_f32 v[4:5], v[212:213], s[16:17], v[4:5] op_sel_hi:[1,0,1]
	v_pk_fma_f32 v[6:7], v[214:215], s[16:17], v[6:7] op_sel_hi:[1,0,1]
	global_store_dwordx4 v140, v[4:7], s[70:71] offset:512
	s_waitcnt vmcnt(7)
	v_pk_add_f32 v[216:217], v[216:217], v[148:149] op_sel_hi:[1,0] neg_lo:[0,1] neg_hi:[0,1]
	v_pk_add_f32 v[218:219], v[218:219], v[148:149] op_sel_hi:[1,0] neg_lo:[0,1] neg_hi:[0,1]
	v_pk_mul_f32 v[216:217], v[216:217], v[148:149] op_sel:[0,1] op_sel_hi:[1,1]
	v_pk_mul_f32 v[218:219], v[218:219], v[148:149] op_sel:[0,1] op_sel_hi:[1,1]
	v_pk_fma_f32 v[216:217], v[216:217], v[170:171], v[190:191]
	v_pk_fma_f32 v[218:219], v[218:219], v[172:173], v[192:193]
	v_pk_fma_f32 v[0:1], v[216:217], s[16:17], v[0:1] op_sel_hi:[1,0,1]
	v_pk_fma_f32 v[2:3], v[218:219], s[16:17], v[2:3] op_sel_hi:[1,0,1]
	global_store_dwordx4 v140, v[0:3], s[70:71] offset:576
	s_branch .Llz_join
